# N12 + full LDS drain (lgkmcnt(0)) before the PREP that follows step loop 3: no look-ahead read can land in a reused register
# baseline (speedup 1.0000x reference)
.LBB0_437:
	v_swap_b32 v93, v94
	v_swap_b32 v33, v34
	s_waitcnt lgkmcnt(0)
	v_pk_mul_f32 v[130:131], v[92:93], v[24:25] op_sel_hi:[1,0]
	v_pk_fma_f32 v[130:131], v[94:95], v[24:25], v[130:131] op_sel:[0,1,0]
	v_pk_fma_f32 v[130:131], v[32:33], v[26:27], v[130:131] op_sel_hi:[1,0,1]
	v_pk_fma_f32 v[130:131], v[34:35], v[26:27], v[130:131] op_sel:[0,1,0]
	ds_read_b128 v[12:15], v113 offset:12288
	ds_read_b128 v[116:119], v113 offset:16384
	ds_read_b128 v[120:123], v113 offset:8192
	ds_read_b128 v[124:127], v113
	ds_read_b64 v[90:91], v112
	v_pk_fma_f32 v[92:93], v[28:29], v[96:97], v[92:93] op_sel_hi:[0,1,1]
	v_pk_fma_f32 v[94:95], v[28:29], v[96:97], v[94:95] op_sel:[1,0,0]
	v_add_f32_dpp v130, v130, v130 quad_perm:[1,0,3,2] row_mask:0xf bank_mask:0xf bound_ctrl:1
	v_add_f32_dpp v131, v131, v131 quad_perm:[1,0,3,2] row_mask:0xf bank_mask:0xf bound_ctrl:1
	v_pk_fma_f32 v[32:33], v[30:31], v[96:97], v[32:33] op_sel_hi:[0,1,1]
	v_add_f32_dpp v130, v130, v130 quad_perm:[2,3,0,1] row_mask:0xf bank_mask:0xf bound_ctrl:1
	v_add_f32_dpp v131, v131, v131 quad_perm:[2,3,0,1] row_mask:0xf bank_mask:0xf bound_ctrl:1
	v_pk_fma_f32 v[34:35], v[30:31], v[96:97], v[34:35] op_sel:[1,0,0]
	v_add_f32_dpp v130, v130, v130 row_half_mirror row_mask:0xf bank_mask:0xf bound_ctrl:1
	v_add_f32_dpp v131, v131, v131 row_half_mirror row_mask:0xf bank_mask:0xf bound_ctrl:1
	ds_read_b64 v[96:97], v115 offset:20736
	v_add_f32_dpp v130, v130, v130 row_mirror row_mask:0xf bank_mask:0xf bound_ctrl:1
	v_add_f32_dpp v131, v131, v131 row_mirror row_mask:0xf bank_mask:0xf bound_ctrl:1
	v_pk_fma_f32 v[92:93], v[20:21], v[130:131], v[92:93] op_sel_hi:[0,1,1]
	v_pk_fma_f32 v[94:95], v[20:21], v[130:131], v[94:95] op_sel:[1,0,0]
	v_pk_fma_f32 v[32:33], v[22:23], v[130:131], v[32:33] op_sel_hi:[0,1,1]
	v_pk_fma_f32 v[34:35], v[22:23], v[130:131], v[34:35] op_sel:[1,0,0]
	s_waitcnt lgkmcnt(1)
	v_pk_mul_f32 v[130:131], v[92:93], v[12:13] op_sel_hi:[1,0]
	v_pk_mul_f32 v[20:21], v[92:93], v[16:17] op_sel_hi:[1,0]
	v_pk_fma_f32 v[130:131], v[94:95], v[12:13], v[130:131] op_sel:[0,1,0]
	v_pk_fma_f32 v[20:21], v[94:95], v[16:17], v[20:21] op_sel:[0,1,0]
	v_pk_fma_f32 v[130:131], v[32:33], v[14:15], v[130:131] op_sel_hi:[1,0,1]
	v_pk_fma_f32 v[20:21], v[32:33], v[18:19], v[20:21] op_sel_hi:[1,0,1]
	v_pk_fma_f32 v[130:131], v[34:35], v[14:15], v[130:131] op_sel:[0,1,0]
	v_pk_fma_f32 v[20:21], v[34:35], v[18:19], v[20:21] op_sel:[0,1,0]
	v_cvt_pk_f16_f32 v14, v20, v21
	v_add_f32_dpp v130, v130, v130 quad_perm:[1,0,3,2] row_mask:0xf bank_mask:0xf bound_ctrl:1
	v_add_f32_dpp v131, v131, v131 quad_perm:[1,0,3,2] row_mask:0xf bank_mask:0xf bound_ctrl:1
	ds_read_b128 v[24:27], v114 offset:12800
	ds_read_b128 v[20:23], v114 offset:16896
	ds_read_b128 v[28:31], v114 offset:8704
	ds_read_b128 v[16:19], v114 offset:512
	v_pk_fma_f32 v[92:93], v[120:121], v[90:91], v[92:93] op_sel_hi:[0,1,1]
	v_add_f32_dpp v130, v130, v130 quad_perm:[2,3,0,1] row_mask:0xf bank_mask:0xf bound_ctrl:1
	v_add_f32_dpp v131, v131, v131 quad_perm:[2,3,0,1] row_mask:0xf bank_mask:0xf bound_ctrl:1
	v_pk_fma_f32 v[94:95], v[120:121], v[90:91], v[94:95] op_sel:[1,0,0]
	v_add_f32_dpp v130, v130, v130 row_half_mirror row_mask:0xf bank_mask:0xf bound_ctrl:1
	v_add_f32_dpp v131, v131, v131 row_half_mirror row_mask:0xf bank_mask:0xf bound_ctrl:1
	v_pk_fma_f32 v[32:33], v[122:123], v[90:91], v[32:33] op_sel_hi:[0,1,1]
	v_pk_fma_f32 v[34:35], v[122:123], v[90:91], v[34:35] op_sel:[1,0,0]
	v_add_f32_dpp v130, v130, v130 row_mirror row_mask:0xf bank_mask:0xf bound_ctrl:1
	v_add_f32_dpp v131, v131, v131 row_mirror row_mask:0xf bank_mask:0xf bound_ctrl:1
	v_pk_fma_f32 v[92:93], v[116:117], v[130:131], v[92:93] op_sel_hi:[0,1,1]
	v_pk_fma_f32 v[94:95], v[116:117], v[130:131], v[94:95] op_sel:[1,0,0]
	v_pk_fma_f32 v[32:33], v[118:119], v[130:131], v[32:33] op_sel_hi:[0,1,1]
	v_pk_fma_f32 v[34:35], v[118:119], v[130:131], v[34:35] op_sel:[1,0,0]
	s_waitcnt lgkmcnt(0)
	v_pk_mul_f32 v[130:131], v[92:93], v[24:25] op_sel_hi:[1,0]
	v_pk_mul_f32 v[12:13], v[92:93], v[124:125] op_sel_hi:[1,0]
	v_pk_fma_f32 v[130:131], v[94:95], v[24:25], v[130:131] op_sel:[0,1,0]
	v_pk_fma_f32 v[12:13], v[94:95], v[124:125], v[12:13] op_sel:[0,1,0]
	v_pk_fma_f32 v[130:131], v[32:33], v[26:27], v[130:131] op_sel_hi:[1,0,1]
	v_pk_fma_f32 v[12:13], v[32:33], v[126:127], v[12:13] op_sel_hi:[1,0,1]
	v_pk_fma_f32 v[130:131], v[34:35], v[26:27], v[130:131] op_sel:[0,1,0]
	v_pk_fma_f32 v[12:13], v[34:35], v[126:127], v[12:13] op_sel:[0,1,0]
	v_cvt_pk_f16_f32 v12, v12, v13
	v_add_f32_dpp v130, v130, v130 quad_perm:[1,0,3,2] row_mask:0xf bank_mask:0xf bound_ctrl:1
	v_add_f32_dpp v131, v131, v131 quad_perm:[1,0,3,2] row_mask:0xf bank_mask:0xf bound_ctrl:1
	ds_write2st64_b32 v47, v14, v12 offset0:0 offset1:4
	ds_read_b128 v[12:15], v113 offset:12800
	ds_read_b128 v[116:119], v113 offset:16896
	ds_read_b128 v[120:123], v113 offset:8704
	ds_read_b128 v[124:127], v113 offset:512
	ds_read_b64 v[90:91], v112 offset:256
	v_pk_fma_f32 v[92:93], v[28:29], v[96:97], v[92:93] op_sel_hi:[0,1,1]
	v_add_f32_dpp v130, v130, v130 quad_perm:[2,3,0,1] row_mask:0xf bank_mask:0xf bound_ctrl:1
	v_add_f32_dpp v131, v131, v131 quad_perm:[2,3,0,1] row_mask:0xf bank_mask:0xf bound_ctrl:1
	v_pk_fma_f32 v[94:95], v[28:29], v[96:97], v[94:95] op_sel:[1,0,0]
	v_add_f32_dpp v130, v130, v130 row_half_mirror row_mask:0xf bank_mask:0xf bound_ctrl:1
	v_add_f32_dpp v131, v131, v131 row_half_mirror row_mask:0xf bank_mask:0xf bound_ctrl:1
	v_pk_fma_f32 v[32:33], v[30:31], v[96:97], v[32:33] op_sel_hi:[0,1,1]
	v_pk_fma_f32 v[34:35], v[30:31], v[96:97], v[34:35] op_sel:[1,0,0]
	ds_read_b64 v[96:97], v115 offset:20992
	v_add_f32_dpp v130, v130, v130 row_mirror row_mask:0xf bank_mask:0xf bound_ctrl:1
	v_add_f32_dpp v131, v131, v131 row_mirror row_mask:0xf bank_mask:0xf bound_ctrl:1
	v_pk_fma_f32 v[92:93], v[20:21], v[130:131], v[92:93] op_sel_hi:[0,1,1]
	v_pk_fma_f32 v[94:95], v[20:21], v[130:131], v[94:95] op_sel:[1,0,0]
	v_pk_fma_f32 v[32:33], v[22:23], v[130:131], v[32:33] op_sel_hi:[0,1,1]
	v_pk_fma_f32 v[34:35], v[22:23], v[130:131], v[34:35] op_sel:[1,0,0]
	s_waitcnt lgkmcnt(1)
	v_pk_mul_f32 v[130:131], v[92:93], v[12:13] op_sel_hi:[1,0]
	v_pk_mul_f32 v[20:21], v[92:93], v[16:17] op_sel_hi:[1,0]
	v_pk_fma_f32 v[130:131], v[94:95], v[12:13], v[130:131] op_sel:[0,1,0]
	v_pk_fma_f32 v[20:21], v[94:95], v[16:17], v[20:21] op_sel:[0,1,0]
	v_pk_fma_f32 v[130:131], v[32:33], v[14:15], v[130:131] op_sel_hi:[1,0,1]
	v_pk_fma_f32 v[20:21], v[32:33], v[18:19], v[20:21] op_sel_hi:[1,0,1]
	v_pk_fma_f32 v[130:131], v[34:35], v[14:15], v[130:131] op_sel:[0,1,0]
	v_pk_fma_f32 v[20:21], v[34:35], v[18:19], v[20:21] op_sel:[0,1,0]
	v_cvt_pk_f16_f32 v14, v20, v21
	v_add_f32_dpp v130, v130, v130 quad_perm:[1,0,3,2] row_mask:0xf bank_mask:0xf bound_ctrl:1
	v_add_f32_dpp v131, v131, v131 quad_perm:[1,0,3,2] row_mask:0xf bank_mask:0xf bound_ctrl:1
	ds_read_b128 v[24:27], v114 offset:13312
	ds_read_b128 v[20:23], v114 offset:17408
	ds_read_b128 v[28:31], v114 offset:9216
	ds_read_b128 v[16:19], v114 offset:1024
	v_pk_fma_f32 v[92:93], v[120:121], v[90:91], v[92:93] op_sel_hi:[0,1,1]
	v_add_f32_dpp v130, v130, v130 quad_perm:[2,3,0,1] row_mask:0xf bank_mask:0xf bound_ctrl:1
	v_add_f32_dpp v131, v131, v131 quad_perm:[2,3,0,1] row_mask:0xf bank_mask:0xf bound_ctrl:1
	v_pk_fma_f32 v[94:95], v[120:121], v[90:91], v[94:95] op_sel:[1,0,0]
	v_add_f32_dpp v130, v130, v130 row_half_mirror row_mask:0xf bank_mask:0xf bound_ctrl:1
	v_add_f32_dpp v131, v131, v131 row_half_mirror row_mask:0xf bank_mask:0xf bound_ctrl:1
	v_pk_fma_f32 v[32:33], v[122:123], v[90:91], v[32:33] op_sel_hi:[0,1,1]
	v_pk_fma_f32 v[34:35], v[122:123], v[90:91], v[34:35] op_sel:[1,0,0]
	v_add_f32_dpp v130, v130, v130 row_mirror row_mask:0xf bank_mask:0xf bound_ctrl:1
	v_add_f32_dpp v131, v131, v131 row_mirror row_mask:0xf bank_mask:0xf bound_ctrl:1
	v_pk_fma_f32 v[92:93], v[116:117], v[130:131], v[92:93] op_sel_hi:[0,1,1]
	v_pk_fma_f32 v[94:95], v[116:117], v[130:131], v[94:95] op_sel:[1,0,0]
	v_pk_fma_f32 v[32:33], v[118:119], v[130:131], v[32:33] op_sel_hi:[0,1,1]
	v_pk_fma_f32 v[34:35], v[118:119], v[130:131], v[34:35] op_sel:[1,0,0]
	s_waitcnt lgkmcnt(0)
	v_pk_mul_f32 v[130:131], v[92:93], v[24:25] op_sel_hi:[1,0]
	v_pk_mul_f32 v[12:13], v[92:93], v[124:125] op_sel_hi:[1,0]
	v_pk_fma_f32 v[130:131], v[94:95], v[24:25], v[130:131] op_sel:[0,1,0]
	v_pk_fma_f32 v[12:13], v[94:95], v[124:125], v[12:13] op_sel:[0,1,0]
	v_pk_fma_f32 v[130:131], v[32:33], v[26:27], v[130:131] op_sel_hi:[1,0,1]
	v_pk_fma_f32 v[12:13], v[32:33], v[126:127], v[12:13] op_sel_hi:[1,0,1]
	v_pk_fma_f32 v[130:131], v[34:35], v[26:27], v[130:131] op_sel:[0,1,0]
	v_pk_fma_f32 v[12:13], v[34:35], v[126:127], v[12:13] op_sel:[0,1,0]
	v_cvt_pk_f16_f32 v12, v12, v13
	v_add_f32_dpp v130, v130, v130 quad_perm:[1,0,3,2] row_mask:0xf bank_mask:0xf bound_ctrl:1
	v_add_f32_dpp v131, v131, v131 quad_perm:[1,0,3,2] row_mask:0xf bank_mask:0xf bound_ctrl:1
	ds_write2st64_b32 v47, v14, v12 offset0:8 offset1:12
	ds_read_b128 v[12:15], v113 offset:13312
	ds_read_b128 v[116:119], v113 offset:17408
	ds_read_b128 v[120:123], v113 offset:9216
	ds_read_b128 v[124:127], v113 offset:1024
	ds_read_b64 v[90:91], v112 offset:512
	v_pk_fma_f32 v[92:93], v[28:29], v[96:97], v[92:93] op_sel_hi:[0,1,1]
	v_add_f32_dpp v130, v130, v130 quad_perm:[2,3,0,1] row_mask:0xf bank_mask:0xf bound_ctrl:1
	v_add_f32_dpp v131, v131, v131 quad_perm:[2,3,0,1] row_mask:0xf bank_mask:0xf bound_ctrl:1
	v_pk_fma_f32 v[94:95], v[28:29], v[96:97], v[94:95] op_sel:[1,0,0]
	v_add_f32_dpp v130, v130, v130 row_half_mirror row_mask:0xf bank_mask:0xf bound_ctrl:1
	v_add_f32_dpp v131, v131, v131 row_half_mirror row_mask:0xf bank_mask:0xf bound_ctrl:1
	v_pk_fma_f32 v[32:33], v[30:31], v[96:97], v[32:33] op_sel_hi:[0,1,1]
	v_pk_fma_f32 v[34:35], v[30:31], v[96:97], v[34:35] op_sel:[1,0,0]
	ds_read_b64 v[96:97], v115 offset:21248
	v_add_f32_dpp v130, v130, v130 row_mirror row_mask:0xf bank_mask:0xf bound_ctrl:1
	v_add_f32_dpp v131, v131, v131 row_mirror row_mask:0xf bank_mask:0xf bound_ctrl:1
	v_pk_fma_f32 v[92:93], v[20:21], v[130:131], v[92:93] op_sel_hi:[0,1,1]
	v_pk_fma_f32 v[94:95], v[20:21], v[130:131], v[94:95] op_sel:[1,0,0]
	v_pk_fma_f32 v[32:33], v[22:23], v[130:131], v[32:33] op_sel_hi:[0,1,1]
	v_pk_fma_f32 v[34:35], v[22:23], v[130:131], v[34:35] op_sel:[1,0,0]
	s_waitcnt lgkmcnt(1)
	v_pk_mul_f32 v[130:131], v[92:93], v[12:13] op_sel_hi:[1,0]
	v_pk_mul_f32 v[20:21], v[92:93], v[16:17] op_sel_hi:[1,0]
	v_pk_fma_f32 v[130:131], v[94:95], v[12:13], v[130:131] op_sel:[0,1,0]
	v_pk_fma_f32 v[20:21], v[94:95], v[16:17], v[20:21] op_sel:[0,1,0]
	v_pk_fma_f32 v[130:131], v[32:33], v[14:15], v[130:131] op_sel_hi:[1,0,1]
	v_pk_fma_f32 v[20:21], v[32:33], v[18:19], v[20:21] op_sel_hi:[1,0,1]
	v_pk_fma_f32 v[130:131], v[34:35], v[14:15], v[130:131] op_sel:[0,1,0]
	v_pk_fma_f32 v[20:21], v[34:35], v[18:19], v[20:21] op_sel:[0,1,0]
	v_cvt_pk_f16_f32 v14, v20, v21
	v_add_f32_dpp v130, v130, v130 quad_perm:[1,0,3,2] row_mask:0xf bank_mask:0xf bound_ctrl:1
	v_add_f32_dpp v131, v131, v131 quad_perm:[1,0,3,2] row_mask:0xf bank_mask:0xf bound_ctrl:1
	ds_read_b128 v[24:27], v114 offset:13824
	ds_read_b128 v[20:23], v114 offset:17920
	ds_read_b128 v[28:31], v114 offset:9728
	ds_read_b128 v[16:19], v114 offset:1536
	v_pk_fma_f32 v[92:93], v[120:121], v[90:91], v[92:93] op_sel_hi:[0,1,1]
	v_add_f32_dpp v130, v130, v130 quad_perm:[2,3,0,1] row_mask:0xf bank_mask:0xf bound_ctrl:1
	v_add_f32_dpp v131, v131, v131 quad_perm:[2,3,0,1] row_mask:0xf bank_mask:0xf bound_ctrl:1
	v_pk_fma_f32 v[94:95], v[120:121], v[90:91], v[94:95] op_sel:[1,0,0]
	v_add_f32_dpp v130, v130, v130 row_half_mirror row_mask:0xf bank_mask:0xf bound_ctrl:1
	v_add_f32_dpp v131, v131, v131 row_half_mirror row_mask:0xf bank_mask:0xf bound_ctrl:1
	v_pk_fma_f32 v[32:33], v[122:123], v[90:91], v[32:33] op_sel_hi:[0,1,1]
	v_pk_fma_f32 v[34:35], v[122:123], v[90:91], v[34:35] op_sel:[1,0,0]
	v_add_f32_dpp v130, v130, v130 row_mirror row_mask:0xf bank_mask:0xf bound_ctrl:1
	v_add_f32_dpp v131, v131, v131 row_mirror row_mask:0xf bank_mask:0xf bound_ctrl:1
	v_pk_fma_f32 v[92:93], v[116:117], v[130:131], v[92:93] op_sel_hi:[0,1,1]
	v_pk_fma_f32 v[94:95], v[116:117], v[130:131], v[94:95] op_sel:[1,0,0]
	v_pk_fma_f32 v[32:33], v[118:119], v[130:131], v[32:33] op_sel_hi:[0,1,1]
	v_pk_fma_f32 v[34:35], v[118:119], v[130:131], v[34:35] op_sel:[1,0,0]
	s_waitcnt lgkmcnt(0)
	v_pk_mul_f32 v[130:131], v[92:93], v[24:25] op_sel_hi:[1,0]
	v_pk_mul_f32 v[12:13], v[92:93], v[124:125] op_sel_hi:[1,0]
	v_pk_fma_f32 v[130:131], v[94:95], v[24:25], v[130:131] op_sel:[0,1,0]
	v_pk_fma_f32 v[12:13], v[94:95], v[124:125], v[12:13] op_sel:[0,1,0]
	v_pk_fma_f32 v[130:131], v[32:33], v[26:27], v[130:131] op_sel_hi:[1,0,1]
	v_pk_fma_f32 v[12:13], v[32:33], v[126:127], v[12:13] op_sel_hi:[1,0,1]
	v_pk_fma_f32 v[130:131], v[34:35], v[26:27], v[130:131] op_sel:[0,1,0]
	v_pk_fma_f32 v[12:13], v[34:35], v[126:127], v[12:13] op_sel:[0,1,0]
	v_cvt_pk_f16_f32 v12, v12, v13
	v_add_f32_dpp v130, v130, v130 quad_perm:[1,0,3,2] row_mask:0xf bank_mask:0xf bound_ctrl:1
	v_add_f32_dpp v131, v131, v131 quad_perm:[1,0,3,2] row_mask:0xf bank_mask:0xf bound_ctrl:1
	ds_write2st64_b32 v47, v14, v12 offset0:16 offset1:20
	ds_read_b128 v[12:15], v113 offset:13824
	ds_read_b128 v[116:119], v113 offset:17920
	ds_read_b128 v[120:123], v113 offset:9728
	ds_read_b128 v[124:127], v113 offset:1536
	ds_read_b64 v[90:91], v112 offset:768
	v_pk_fma_f32 v[92:93], v[28:29], v[96:97], v[92:93] op_sel_hi:[0,1,1]
	v_add_f32_dpp v130, v130, v130 quad_perm:[2,3,0,1] row_mask:0xf bank_mask:0xf bound_ctrl:1
	v_add_f32_dpp v131, v131, v131 quad_perm:[2,3,0,1] row_mask:0xf bank_mask:0xf bound_ctrl:1
	v_pk_fma_f32 v[94:95], v[28:29], v[96:97], v[94:95] op_sel:[1,0,0]
	v_add_f32_dpp v130, v130, v130 row_half_mirror row_mask:0xf bank_mask:0xf bound_ctrl:1
	v_add_f32_dpp v131, v131, v131 row_half_mirror row_mask:0xf bank_mask:0xf bound_ctrl:1
	v_pk_fma_f32 v[32:33], v[30:31], v[96:97], v[32:33] op_sel_hi:[0,1,1]
	v_pk_fma_f32 v[34:35], v[30:31], v[96:97], v[34:35] op_sel:[1,0,0]
	ds_read_b64 v[96:97], v115 offset:21504
	v_add_f32_dpp v130, v130, v130 row_mirror row_mask:0xf bank_mask:0xf bound_ctrl:1
	v_add_f32_dpp v131, v131, v131 row_mirror row_mask:0xf bank_mask:0xf bound_ctrl:1
	v_pk_fma_f32 v[92:93], v[20:21], v[130:131], v[92:93] op_sel_hi:[0,1,1]
	v_pk_fma_f32 v[94:95], v[20:21], v[130:131], v[94:95] op_sel:[1,0,0]
	v_pk_fma_f32 v[32:33], v[22:23], v[130:131], v[32:33] op_sel_hi:[0,1,1]
	v_pk_fma_f32 v[34:35], v[22:23], v[130:131], v[34:35] op_sel:[1,0,0]
	s_waitcnt lgkmcnt(1)
	v_pk_mul_f32 v[130:131], v[92:93], v[12:13] op_sel_hi:[1,0]
	v_pk_mul_f32 v[20:21], v[92:93], v[16:17] op_sel_hi:[1,0]
	v_pk_fma_f32 v[130:131], v[94:95], v[12:13], v[130:131] op_sel:[0,1,0]
	v_pk_fma_f32 v[20:21], v[94:95], v[16:17], v[20:21] op_sel:[0,1,0]
	v_pk_fma_f32 v[130:131], v[32:33], v[14:15], v[130:131] op_sel_hi:[1,0,1]
	v_pk_fma_f32 v[20:21], v[32:33], v[18:19], v[20:21] op_sel_hi:[1,0,1]
	v_pk_fma_f32 v[130:131], v[34:35], v[14:15], v[130:131] op_sel:[0,1,0]
	v_pk_fma_f32 v[20:21], v[34:35], v[18:19], v[20:21] op_sel:[0,1,0]
	v_cvt_pk_f16_f32 v14, v20, v21
	v_add_f32_dpp v130, v130, v130 quad_perm:[1,0,3,2] row_mask:0xf bank_mask:0xf bound_ctrl:1
	v_add_f32_dpp v131, v131, v131 quad_perm:[1,0,3,2] row_mask:0xf bank_mask:0xf bound_ctrl:1
	ds_read_b128 v[24:27], v114 offset:14336
	ds_read_b128 v[20:23], v114 offset:18432
	ds_read_b128 v[28:31], v114 offset:10240
	ds_read_b128 v[16:19], v114 offset:2048
	v_pk_fma_f32 v[92:93], v[120:121], v[90:91], v[92:93] op_sel_hi:[0,1,1]
	v_add_f32_dpp v130, v130, v130 quad_perm:[2,3,0,1] row_mask:0xf bank_mask:0xf bound_ctrl:1
	v_add_f32_dpp v131, v131, v131 quad_perm:[2,3,0,1] row_mask:0xf bank_mask:0xf bound_ctrl:1
	v_pk_fma_f32 v[94:95], v[120:121], v[90:91], v[94:95] op_sel:[1,0,0]
	v_add_f32_dpp v130, v130, v130 row_half_mirror row_mask:0xf bank_mask:0xf bound_ctrl:1
	v_add_f32_dpp v131, v131, v131 row_half_mirror row_mask:0xf bank_mask:0xf bound_ctrl:1
	v_pk_fma_f32 v[32:33], v[122:123], v[90:91], v[32:33] op_sel_hi:[0,1,1]
	v_pk_fma_f32 v[34:35], v[122:123], v[90:91], v[34:35] op_sel:[1,0,0]
	v_add_f32_dpp v130, v130, v130 row_mirror row_mask:0xf bank_mask:0xf bound_ctrl:1
	v_add_f32_dpp v131, v131, v131 row_mirror row_mask:0xf bank_mask:0xf bound_ctrl:1
	v_pk_fma_f32 v[92:93], v[116:117], v[130:131], v[92:93] op_sel_hi:[0,1,1]
	v_pk_fma_f32 v[94:95], v[116:117], v[130:131], v[94:95] op_sel:[1,0,0]
	v_pk_fma_f32 v[32:33], v[118:119], v[130:131], v[32:33] op_sel_hi:[0,1,1]
	v_pk_fma_f32 v[34:35], v[118:119], v[130:131], v[34:35] op_sel:[1,0,0]
	s_waitcnt lgkmcnt(0)
	v_pk_mul_f32 v[130:131], v[92:93], v[24:25] op_sel_hi:[1,0]
	v_pk_mul_f32 v[12:13], v[92:93], v[124:125] op_sel_hi:[1,0]
	v_pk_fma_f32 v[130:131], v[94:95], v[24:25], v[130:131] op_sel:[0,1,0]
	v_pk_fma_f32 v[12:13], v[94:95], v[124:125], v[12:13] op_sel:[0,1,0]
	v_pk_fma_f32 v[130:131], v[32:33], v[26:27], v[130:131] op_sel_hi:[1,0,1]
	v_pk_fma_f32 v[12:13], v[32:33], v[126:127], v[12:13] op_sel_hi:[1,0,1]
	v_pk_fma_f32 v[130:131], v[34:35], v[26:27], v[130:131] op_sel:[0,1,0]
	v_pk_fma_f32 v[12:13], v[34:35], v[126:127], v[12:13] op_sel:[0,1,0]
	v_cvt_pk_f16_f32 v12, v12, v13
	v_add_f32_dpp v130, v130, v130 quad_perm:[1,0,3,2] row_mask:0xf bank_mask:0xf bound_ctrl:1
	v_add_f32_dpp v131, v131, v131 quad_perm:[1,0,3,2] row_mask:0xf bank_mask:0xf bound_ctrl:1
	ds_write2st64_b32 v47, v14, v12 offset0:24 offset1:28
	ds_read_b128 v[12:15], v113 offset:14336
	ds_read_b128 v[116:119], v113 offset:18432
	ds_read_b128 v[120:123], v113 offset:10240
	ds_read_b128 v[124:127], v113 offset:2048
	ds_read_b64 v[90:91], v112 offset:1024
	v_pk_fma_f32 v[92:93], v[28:29], v[96:97], v[92:93] op_sel_hi:[0,1,1]
	v_add_f32_dpp v130, v130, v130 quad_perm:[2,3,0,1] row_mask:0xf bank_mask:0xf bound_ctrl:1
	v_add_f32_dpp v131, v131, v131 quad_perm:[2,3,0,1] row_mask:0xf bank_mask:0xf bound_ctrl:1
	v_pk_fma_f32 v[94:95], v[28:29], v[96:97], v[94:95] op_sel:[1,0,0]
	v_add_f32_dpp v130, v130, v130 row_half_mirror row_mask:0xf bank_mask:0xf bound_ctrl:1
	v_add_f32_dpp v131, v131, v131 row_half_mirror row_mask:0xf bank_mask:0xf bound_ctrl:1
	v_pk_fma_f32 v[32:33], v[30:31], v[96:97], v[32:33] op_sel_hi:[0,1,1]
	v_pk_fma_f32 v[34:35], v[30:31], v[96:97], v[34:35] op_sel:[1,0,0]
	ds_read_b64 v[96:97], v115 offset:21760
	v_add_f32_dpp v130, v130, v130 row_mirror row_mask:0xf bank_mask:0xf bound_ctrl:1
	v_add_f32_dpp v131, v131, v131 row_mirror row_mask:0xf bank_mask:0xf bound_ctrl:1
	v_pk_fma_f32 v[92:93], v[20:21], v[130:131], v[92:93] op_sel_hi:[0,1,1]
	v_pk_fma_f32 v[94:95], v[20:21], v[130:131], v[94:95] op_sel:[1,0,0]
	v_pk_fma_f32 v[32:33], v[22:23], v[130:131], v[32:33] op_sel_hi:[0,1,1]
	v_pk_fma_f32 v[34:35], v[22:23], v[130:131], v[34:35] op_sel:[1,0,0]
	s_waitcnt lgkmcnt(1)
	v_pk_mul_f32 v[130:131], v[92:93], v[12:13] op_sel_hi:[1,0]
	v_pk_mul_f32 v[20:21], v[92:93], v[16:17] op_sel_hi:[1,0]
	v_pk_fma_f32 v[130:131], v[94:95], v[12:13], v[130:131] op_sel:[0,1,0]
	v_pk_fma_f32 v[20:21], v[94:95], v[16:17], v[20:21] op_sel:[0,1,0]
	v_pk_fma_f32 v[130:131], v[32:33], v[14:15], v[130:131] op_sel_hi:[1,0,1]
	v_pk_fma_f32 v[20:21], v[32:33], v[18:19], v[20:21] op_sel_hi:[1,0,1]
	v_pk_fma_f32 v[130:131], v[34:35], v[14:15], v[130:131] op_sel:[0,1,0]
	v_pk_fma_f32 v[20:21], v[34:35], v[18:19], v[20:21] op_sel:[0,1,0]
	v_cvt_pk_f16_f32 v14, v20, v21
	v_add_f32_dpp v130, v130, v130 quad_perm:[1,0,3,2] row_mask:0xf bank_mask:0xf bound_ctrl:1
	v_add_f32_dpp v131, v131, v131 quad_perm:[1,0,3,2] row_mask:0xf bank_mask:0xf bound_ctrl:1
	ds_read_b128 v[24:27], v114 offset:14848
	ds_read_b128 v[20:23], v114 offset:18944
	ds_read_b128 v[28:31], v114 offset:10752
	ds_read_b128 v[16:19], v114 offset:2560
	v_pk_fma_f32 v[92:93], v[120:121], v[90:91], v[92:93] op_sel_hi:[0,1,1]
	v_add_f32_dpp v130, v130, v130 quad_perm:[2,3,0,1] row_mask:0xf bank_mask:0xf bound_ctrl:1
	v_add_f32_dpp v131, v131, v131 quad_perm:[2,3,0,1] row_mask:0xf bank_mask:0xf bound_ctrl:1
	v_pk_fma_f32 v[94:95], v[120:121], v[90:91], v[94:95] op_sel:[1,0,0]
	v_add_f32_dpp v130, v130, v130 row_half_mirror row_mask:0xf bank_mask:0xf bound_ctrl:1
	v_add_f32_dpp v131, v131, v131 row_half_mirror row_mask:0xf bank_mask:0xf bound_ctrl:1
	v_pk_fma_f32 v[32:33], v[122:123], v[90:91], v[32:33] op_sel_hi:[0,1,1]
	v_pk_fma_f32 v[34:35], v[122:123], v[90:91], v[34:35] op_sel:[1,0,0]
	v_add_f32_dpp v130, v130, v130 row_mirror row_mask:0xf bank_mask:0xf bound_ctrl:1
	v_add_f32_dpp v131, v131, v131 row_mirror row_mask:0xf bank_mask:0xf bound_ctrl:1
	v_pk_fma_f32 v[92:93], v[116:117], v[130:131], v[92:93] op_sel_hi:[0,1,1]
	v_pk_fma_f32 v[94:95], v[116:117], v[130:131], v[94:95] op_sel:[1,0,0]
	v_pk_fma_f32 v[32:33], v[118:119], v[130:131], v[32:33] op_sel_hi:[0,1,1]
	v_pk_fma_f32 v[34:35], v[118:119], v[130:131], v[34:35] op_sel:[1,0,0]
	s_waitcnt lgkmcnt(0)
	v_pk_mul_f32 v[130:131], v[92:93], v[24:25] op_sel_hi:[1,0]
	v_pk_mul_f32 v[12:13], v[92:93], v[124:125] op_sel_hi:[1,0]
	v_pk_fma_f32 v[130:131], v[94:95], v[24:25], v[130:131] op_sel:[0,1,0]
	v_pk_fma_f32 v[12:13], v[94:95], v[124:125], v[12:13] op_sel:[0,1,0]
	v_pk_fma_f32 v[130:131], v[32:33], v[26:27], v[130:131] op_sel_hi:[1,0,1]
	v_pk_fma_f32 v[12:13], v[32:33], v[126:127], v[12:13] op_sel_hi:[1,0,1]
	v_pk_fma_f32 v[130:131], v[34:35], v[26:27], v[130:131] op_sel:[0,1,0]
	v_pk_fma_f32 v[12:13], v[34:35], v[126:127], v[12:13] op_sel:[0,1,0]
	v_cvt_pk_f16_f32 v12, v12, v13
	v_add_f32_dpp v130, v130, v130 quad_perm:[1,0,3,2] row_mask:0xf bank_mask:0xf bound_ctrl:1
	v_add_f32_dpp v131, v131, v131 quad_perm:[1,0,3,2] row_mask:0xf bank_mask:0xf bound_ctrl:1
	ds_write2st64_b32 v47, v14, v12 offset0:32 offset1:36
	ds_read_b128 v[12:15], v113 offset:14848
	ds_read_b128 v[116:119], v113 offset:18944
	ds_read_b128 v[120:123], v113 offset:10752
	ds_read_b128 v[124:127], v113 offset:2560
	ds_read_b64 v[90:91], v112 offset:1280
	v_pk_fma_f32 v[92:93], v[28:29], v[96:97], v[92:93] op_sel_hi:[0,1,1]
	v_add_f32_dpp v130, v130, v130 quad_perm:[2,3,0,1] row_mask:0xf bank_mask:0xf bound_ctrl:1
	v_add_f32_dpp v131, v131, v131 quad_perm:[2,3,0,1] row_mask:0xf bank_mask:0xf bound_ctrl:1
	v_pk_fma_f32 v[94:95], v[28:29], v[96:97], v[94:95] op_sel:[1,0,0]
	v_add_f32_dpp v130, v130, v130 row_half_mirror row_mask:0xf bank_mask:0xf bound_ctrl:1
	v_add_f32_dpp v131, v131, v131 row_half_mirror row_mask:0xf bank_mask:0xf bound_ctrl:1
	v_pk_fma_f32 v[32:33], v[30:31], v[96:97], v[32:33] op_sel_hi:[0,1,1]
	v_pk_fma_f32 v[34:35], v[30:31], v[96:97], v[34:35] op_sel:[1,0,0]
	ds_read_b64 v[96:97], v115 offset:22016
	v_add_f32_dpp v130, v130, v130 row_mirror row_mask:0xf bank_mask:0xf bound_ctrl:1
	v_add_f32_dpp v131, v131, v131 row_mirror row_mask:0xf bank_mask:0xf bound_ctrl:1
	v_pk_fma_f32 v[92:93], v[20:21], v[130:131], v[92:93] op_sel_hi:[0,1,1]
	v_pk_fma_f32 v[94:95], v[20:21], v[130:131], v[94:95] op_sel:[1,0,0]
	v_pk_fma_f32 v[32:33], v[22:23], v[130:131], v[32:33] op_sel_hi:[0,1,1]
	v_pk_fma_f32 v[34:35], v[22:23], v[130:131], v[34:35] op_sel:[1,0,0]
	s_waitcnt lgkmcnt(1)
	v_pk_mul_f32 v[130:131], v[92:93], v[12:13] op_sel_hi:[1,0]
	v_pk_mul_f32 v[20:21], v[92:93], v[16:17] op_sel_hi:[1,0]
	v_pk_fma_f32 v[130:131], v[94:95], v[12:13], v[130:131] op_sel:[0,1,0]
	v_pk_fma_f32 v[20:21], v[94:95], v[16:17], v[20:21] op_sel:[0,1,0]
	v_pk_fma_f32 v[130:131], v[32:33], v[14:15], v[130:131] op_sel_hi:[1,0,1]
	v_pk_fma_f32 v[20:21], v[32:33], v[18:19], v[20:21] op_sel_hi:[1,0,1]
	v_pk_fma_f32 v[130:131], v[34:35], v[14:15], v[130:131] op_sel:[0,1,0]
	v_pk_fma_f32 v[20:21], v[34:35], v[18:19], v[20:21] op_sel:[0,1,0]
	v_cvt_pk_f16_f32 v14, v20, v21
	v_add_f32_dpp v130, v130, v130 quad_perm:[1,0,3,2] row_mask:0xf bank_mask:0xf bound_ctrl:1
	v_add_f32_dpp v131, v131, v131 quad_perm:[1,0,3,2] row_mask:0xf bank_mask:0xf bound_ctrl:1
	ds_read_b128 v[24:27], v114 offset:15360
	ds_read_b128 v[20:23], v114 offset:19456
	ds_read_b128 v[28:31], v114 offset:11264
	ds_read_b128 v[16:19], v114 offset:3072
	v_pk_fma_f32 v[92:93], v[120:121], v[90:91], v[92:93] op_sel_hi:[0,1,1]
	v_add_f32_dpp v130, v130, v130 quad_perm:[2,3,0,1] row_mask:0xf bank_mask:0xf bound_ctrl:1
	v_add_f32_dpp v131, v131, v131 quad_perm:[2,3,0,1] row_mask:0xf bank_mask:0xf bound_ctrl:1
	v_pk_fma_f32 v[94:95], v[120:121], v[90:91], v[94:95] op_sel:[1,0,0]
	v_add_f32_dpp v130, v130, v130 row_half_mirror row_mask:0xf bank_mask:0xf bound_ctrl:1
	v_add_f32_dpp v131, v131, v131 row_half_mirror row_mask:0xf bank_mask:0xf bound_ctrl:1
	v_pk_fma_f32 v[32:33], v[122:123], v[90:91], v[32:33] op_sel_hi:[0,1,1]
	v_pk_fma_f32 v[34:35], v[122:123], v[90:91], v[34:35] op_sel:[1,0,0]
	v_add_f32_dpp v130, v130, v130 row_mirror row_mask:0xf bank_mask:0xf bound_ctrl:1
	v_add_f32_dpp v131, v131, v131 row_mirror row_mask:0xf bank_mask:0xf bound_ctrl:1
	v_pk_fma_f32 v[92:93], v[116:117], v[130:131], v[92:93] op_sel_hi:[0,1,1]
	v_pk_fma_f32 v[94:95], v[116:117], v[130:131], v[94:95] op_sel:[1,0,0]
	v_pk_fma_f32 v[32:33], v[118:119], v[130:131], v[32:33] op_sel_hi:[0,1,1]
	v_pk_fma_f32 v[34:35], v[118:119], v[130:131], v[34:35] op_sel:[1,0,0]
	s_waitcnt lgkmcnt(0)
	v_pk_mul_f32 v[130:131], v[92:93], v[24:25] op_sel_hi:[1,0]
	v_pk_mul_f32 v[12:13], v[92:93], v[124:125] op_sel_hi:[1,0]
	v_pk_fma_f32 v[130:131], v[94:95], v[24:25], v[130:131] op_sel:[0,1,0]
	v_pk_fma_f32 v[12:13], v[94:95], v[124:125], v[12:13] op_sel:[0,1,0]
	v_pk_fma_f32 v[130:131], v[32:33], v[26:27], v[130:131] op_sel_hi:[1,0,1]
	v_pk_fma_f32 v[12:13], v[32:33], v[126:127], v[12:13] op_sel_hi:[1,0,1]
	v_pk_fma_f32 v[130:131], v[34:35], v[26:27], v[130:131] op_sel:[0,1,0]
	v_pk_fma_f32 v[12:13], v[34:35], v[126:127], v[12:13] op_sel:[0,1,0]
	v_cvt_pk_f16_f32 v12, v12, v13
	v_add_f32_dpp v130, v130, v130 quad_perm:[1,0,3,2] row_mask:0xf bank_mask:0xf bound_ctrl:1
	v_add_f32_dpp v131, v131, v131 quad_perm:[1,0,3,2] row_mask:0xf bank_mask:0xf bound_ctrl:1
	ds_write2st64_b32 v47, v14, v12 offset0:40 offset1:44
	ds_read_b128 v[12:15], v113 offset:15360
	ds_read_b128 v[116:119], v113 offset:19456
	ds_read_b128 v[120:123], v113 offset:11264
	ds_read_b128 v[124:127], v113 offset:3072
	ds_read_b64 v[90:91], v112 offset:1536
	v_pk_fma_f32 v[92:93], v[28:29], v[96:97], v[92:93] op_sel_hi:[0,1,1]
	v_add_f32_dpp v130, v130, v130 quad_perm:[2,3,0,1] row_mask:0xf bank_mask:0xf bound_ctrl:1
	v_add_f32_dpp v131, v131, v131 quad_perm:[2,3,0,1] row_mask:0xf bank_mask:0xf bound_ctrl:1
	v_pk_fma_f32 v[94:95], v[28:29], v[96:97], v[94:95] op_sel:[1,0,0]
	v_add_f32_dpp v130, v130, v130 row_half_mirror row_mask:0xf bank_mask:0xf bound_ctrl:1
	v_add_f32_dpp v131, v131, v131 row_half_mirror row_mask:0xf bank_mask:0xf bound_ctrl:1
	v_pk_fma_f32 v[32:33], v[30:31], v[96:97], v[32:33] op_sel_hi:[0,1,1]
	v_pk_fma_f32 v[34:35], v[30:31], v[96:97], v[34:35] op_sel:[1,0,0]
	ds_read_b64 v[96:97], v115 offset:22272
	v_add_f32_dpp v130, v130, v130 row_mirror row_mask:0xf bank_mask:0xf bound_ctrl:1
	v_add_f32_dpp v131, v131, v131 row_mirror row_mask:0xf bank_mask:0xf bound_ctrl:1
	v_pk_fma_f32 v[92:93], v[20:21], v[130:131], v[92:93] op_sel_hi:[0,1,1]
	v_pk_fma_f32 v[94:95], v[20:21], v[130:131], v[94:95] op_sel:[1,0,0]
	v_pk_fma_f32 v[32:33], v[22:23], v[130:131], v[32:33] op_sel_hi:[0,1,1]
	v_pk_fma_f32 v[34:35], v[22:23], v[130:131], v[34:35] op_sel:[1,0,0]
	s_waitcnt lgkmcnt(1)
	v_pk_mul_f32 v[130:131], v[92:93], v[12:13] op_sel_hi:[1,0]
	v_pk_mul_f32 v[20:21], v[92:93], v[16:17] op_sel_hi:[1,0]
	v_pk_fma_f32 v[130:131], v[94:95], v[12:13], v[130:131] op_sel:[0,1,0]
	v_pk_fma_f32 v[20:21], v[94:95], v[16:17], v[20:21] op_sel:[0,1,0]
	v_pk_fma_f32 v[130:131], v[32:33], v[14:15], v[130:131] op_sel_hi:[1,0,1]
	v_pk_fma_f32 v[20:21], v[32:33], v[18:19], v[20:21] op_sel_hi:[1,0,1]
	v_pk_fma_f32 v[130:131], v[34:35], v[14:15], v[130:131] op_sel:[0,1,0]
	v_pk_fma_f32 v[20:21], v[34:35], v[18:19], v[20:21] op_sel:[0,1,0]
	v_cvt_pk_f16_f32 v14, v20, v21
	v_add_f32_dpp v130, v130, v130 quad_perm:[1,0,3,2] row_mask:0xf bank_mask:0xf bound_ctrl:1
	v_add_f32_dpp v131, v131, v131 quad_perm:[1,0,3,2] row_mask:0xf bank_mask:0xf bound_ctrl:1
	ds_read_b128 v[24:27], v114 offset:15872
	ds_read_b128 v[20:23], v114 offset:19968
	ds_read_b128 v[28:31], v114 offset:11776
	ds_read_b128 v[16:19], v114 offset:3584
	v_pk_fma_f32 v[92:93], v[120:121], v[90:91], v[92:93] op_sel_hi:[0,1,1]
	v_add_f32_dpp v130, v130, v130 quad_perm:[2,3,0,1] row_mask:0xf bank_mask:0xf bound_ctrl:1
	v_add_f32_dpp v131, v131, v131 quad_perm:[2,3,0,1] row_mask:0xf bank_mask:0xf bound_ctrl:1
	v_pk_fma_f32 v[94:95], v[120:121], v[90:91], v[94:95] op_sel:[1,0,0]
	v_add_f32_dpp v130, v130, v130 row_half_mirror row_mask:0xf bank_mask:0xf bound_ctrl:1
	v_add_f32_dpp v131, v131, v131 row_half_mirror row_mask:0xf bank_mask:0xf bound_ctrl:1
	v_pk_fma_f32 v[32:33], v[122:123], v[90:91], v[32:33] op_sel_hi:[0,1,1]
	v_pk_fma_f32 v[34:35], v[122:123], v[90:91], v[34:35] op_sel:[1,0,0]
	v_add_f32_dpp v130, v130, v130 row_mirror row_mask:0xf bank_mask:0xf bound_ctrl:1
	v_add_f32_dpp v131, v131, v131 row_mirror row_mask:0xf bank_mask:0xf bound_ctrl:1
	v_pk_fma_f32 v[92:93], v[116:117], v[130:131], v[92:93] op_sel_hi:[0,1,1]
	v_pk_fma_f32 v[94:95], v[116:117], v[130:131], v[94:95] op_sel:[1,0,0]
	v_pk_fma_f32 v[32:33], v[118:119], v[130:131], v[32:33] op_sel_hi:[0,1,1]
	v_pk_fma_f32 v[34:35], v[118:119], v[130:131], v[34:35] op_sel:[1,0,0]
	s_waitcnt lgkmcnt(0)
	v_pk_mul_f32 v[130:131], v[92:93], v[24:25] op_sel_hi:[1,0]
	v_pk_mul_f32 v[12:13], v[92:93], v[124:125] op_sel_hi:[1,0]
	v_pk_fma_f32 v[130:131], v[94:95], v[24:25], v[130:131] op_sel:[0,1,0]
	v_pk_fma_f32 v[12:13], v[94:95], v[124:125], v[12:13] op_sel:[0,1,0]
	v_pk_fma_f32 v[130:131], v[32:33], v[26:27], v[130:131] op_sel_hi:[1,0,1]
	v_pk_fma_f32 v[12:13], v[32:33], v[126:127], v[12:13] op_sel_hi:[1,0,1]
	v_pk_fma_f32 v[130:131], v[34:35], v[26:27], v[130:131] op_sel:[0,1,0]
	v_pk_fma_f32 v[12:13], v[34:35], v[126:127], v[12:13] op_sel:[0,1,0]
	v_cvt_pk_f16_f32 v12, v12, v13
	v_add_f32_dpp v130, v130, v130 quad_perm:[1,0,3,2] row_mask:0xf bank_mask:0xf bound_ctrl:1
	v_add_f32_dpp v131, v131, v131 quad_perm:[1,0,3,2] row_mask:0xf bank_mask:0xf bound_ctrl:1
	ds_write2st64_b32 v47, v14, v12 offset0:48 offset1:52
	ds_read_b128 v[12:15], v113 offset:15872
	ds_read_b128 v[116:119], v113 offset:19968
	ds_read_b128 v[120:123], v113 offset:11776
	ds_read_b128 v[124:127], v113 offset:3584
	ds_read_b64 v[90:91], v112 offset:1792
	v_pk_fma_f32 v[92:93], v[28:29], v[96:97], v[92:93] op_sel_hi:[0,1,1]
	v_add_f32_dpp v130, v130, v130 quad_perm:[2,3,0,1] row_mask:0xf bank_mask:0xf bound_ctrl:1
	v_add_f32_dpp v131, v131, v131 quad_perm:[2,3,0,1] row_mask:0xf bank_mask:0xf bound_ctrl:1
	v_pk_fma_f32 v[94:95], v[28:29], v[96:97], v[94:95] op_sel:[1,0,0]
	v_add_f32_dpp v130, v130, v130 row_half_mirror row_mask:0xf bank_mask:0xf bound_ctrl:1
	v_add_f32_dpp v131, v131, v131 row_half_mirror row_mask:0xf bank_mask:0xf bound_ctrl:1
	v_pk_fma_f32 v[32:33], v[30:31], v[96:97], v[32:33] op_sel_hi:[0,1,1]
	v_pk_fma_f32 v[34:35], v[30:31], v[96:97], v[34:35] op_sel:[1,0,0]
	ds_read_b64 v[96:97], v115 offset:22272
	v_add_f32_dpp v130, v130, v130 row_mirror row_mask:0xf bank_mask:0xf bound_ctrl:1
	v_add_f32_dpp v131, v131, v131 row_mirror row_mask:0xf bank_mask:0xf bound_ctrl:1
	v_pk_fma_f32 v[92:93], v[20:21], v[130:131], v[92:93] op_sel_hi:[0,1,1]
	v_pk_fma_f32 v[94:95], v[20:21], v[130:131], v[94:95] op_sel:[1,0,0]
	v_pk_fma_f32 v[32:33], v[22:23], v[130:131], v[32:33] op_sel_hi:[0,1,1]
	v_pk_fma_f32 v[34:35], v[22:23], v[130:131], v[34:35] op_sel:[1,0,0]
	s_waitcnt lgkmcnt(1)
	v_pk_mul_f32 v[130:131], v[92:93], v[12:13] op_sel_hi:[1,0]
	v_pk_mul_f32 v[20:21], v[92:93], v[16:17] op_sel_hi:[1,0]
	v_pk_fma_f32 v[130:131], v[94:95], v[12:13], v[130:131] op_sel:[0,1,0]
	v_pk_fma_f32 v[20:21], v[94:95], v[16:17], v[20:21] op_sel:[0,1,0]
	v_pk_fma_f32 v[130:131], v[32:33], v[14:15], v[130:131] op_sel_hi:[1,0,1]
	v_pk_fma_f32 v[20:21], v[32:33], v[18:19], v[20:21] op_sel_hi:[1,0,1]
	v_pk_fma_f32 v[130:131], v[34:35], v[14:15], v[130:131] op_sel:[0,1,0]
	v_pk_fma_f32 v[20:21], v[34:35], v[18:19], v[20:21] op_sel:[0,1,0]
	v_cvt_pk_f16_f32 v14, v20, v21
	v_add_f32_dpp v130, v130, v130 quad_perm:[1,0,3,2] row_mask:0xf bank_mask:0xf bound_ctrl:1
	v_add_f32_dpp v131, v131, v131 quad_perm:[1,0,3,2] row_mask:0xf bank_mask:0xf bound_ctrl:1
	ds_read_b128 v[24:27], v114 offset:15872
	ds_read_b128 v[20:23], v114 offset:19968
	ds_read_b128 v[28:31], v114 offset:11776
	ds_read_b128 v[16:19], v114 offset:3584
	v_pk_fma_f32 v[92:93], v[120:121], v[90:91], v[92:93] op_sel_hi:[0,1,1]
	v_add_f32_dpp v130, v130, v130 quad_perm:[2,3,0,1] row_mask:0xf bank_mask:0xf bound_ctrl:1
	v_add_f32_dpp v131, v131, v131 quad_perm:[2,3,0,1] row_mask:0xf bank_mask:0xf bound_ctrl:1
	v_pk_fma_f32 v[94:95], v[120:121], v[90:91], v[94:95] op_sel:[1,0,0]
	v_add_f32_dpp v130, v130, v130 row_half_mirror row_mask:0xf bank_mask:0xf bound_ctrl:1
	v_add_f32_dpp v131, v131, v131 row_half_mirror row_mask:0xf bank_mask:0xf bound_ctrl:1
	v_pk_fma_f32 v[32:33], v[122:123], v[90:91], v[32:33] op_sel_hi:[0,1,1]
	v_pk_fma_f32 v[34:35], v[122:123], v[90:91], v[34:35] op_sel:[1,0,0]
	v_add_f32_dpp v130, v130, v130 row_mirror row_mask:0xf bank_mask:0xf bound_ctrl:1
	v_add_f32_dpp v131, v131, v131 row_mirror row_mask:0xf bank_mask:0xf bound_ctrl:1
	v_pk_fma_f32 v[92:93], v[116:117], v[130:131], v[92:93] op_sel_hi:[0,1,1]
	v_pk_fma_f32 v[94:95], v[116:117], v[130:131], v[94:95] op_sel:[1,0,0]
	v_pk_fma_f32 v[32:33], v[118:119], v[130:131], v[32:33] op_sel_hi:[0,1,1]
	v_pk_fma_f32 v[34:35], v[118:119], v[130:131], v[34:35] op_sel:[1,0,0]
	v_pk_mul_f32 v[12:13], v[92:93], v[124:125] op_sel_hi:[1,0]
	v_pk_fma_f32 v[12:13], v[94:95], v[124:125], v[12:13] op_sel:[0,1,0]
	v_pk_fma_f32 v[12:13], v[32:33], v[126:127], v[12:13] op_sel_hi:[1,0,1]
	v_pk_fma_f32 v[12:13], v[34:35], v[126:127], v[12:13] op_sel:[0,1,0]
	v_cvt_pk_f16_f32 v12, v12, v13
	ds_write2st64_b32 v47, v14, v12 offset0:56 offset1:60
	v_swap_b32 v93, v94
	v_swap_b32 v33, v34
	ds_read_b128 v[12:15], v114 offset:7936
	s_add_i32 s93, s93, 3
	s_and_b64 vcc, exec, s[82:83]
	s_cbranch_vccz .LBB0_409
	s_waitcnt lgkmcnt(0)
	v_cvt_f32_f16_sdwa v29, v50 dst_sel:DWORD dst_unused:UNUSED_PAD src0_sel:WORD_1
	v_cvt_f32_f16_e32 v28, v50
	v_cvt_f32_f16_sdwa v31, v51 dst_sel:DWORD dst_unused:UNUSED_PAD src0_sel:WORD_1
	v_cvt_f32_f16_e32 v30, v51
	s_waitcnt lgkmcnt(3)
	v_cvt_f32_f16_sdwa v17, v56 dst_sel:DWORD dst_unused:UNUSED_PAD src0_sel:WORD_1
	v_cvt_f32_f16_e32 v16, v56
	v_cvt_f32_f16_sdwa v19, v57 dst_sel:DWORD dst_unused:UNUSED_PAD src0_sel:WORD_1
	v_cvt_f32_f16_e32 v18, v57
	v_pk_mul_f32 v[22:23], v[0:1], v[28:29]
	v_pk_mul_f32 v[20:21], v[2:3], v[30:31]
	s_waitcnt lgkmcnt(2)
	v_pk_mul_f32 v[96:97], v[22:23], v[22:23]
	v_pk_mul_f32 v[90:91], v[20:21], v[20:21]
	v_add_f32_e32 v42, v96, v97
	v_cvt_f32_f16_sdwa v25, v48 dst_sel:DWORD dst_unused:UNUSED_PAD src0_sel:WORD_1
	v_cvt_f32_f16_e32 v24, v48
	v_cvt_f32_f16_sdwa v27, v49 dst_sel:DWORD dst_unused:UNUSED_PAD src0_sel:WORD_1
	v_cvt_f32_f16_e32 v26, v49
	v_add_f32_e32 v42, v90, v42
	v_add_f32_e32 v42, v91, v42
	v_pk_add_f32 v[90:91], v[16:17], -1.0 op_sel_hi:[1,0]
	v_pk_add_f32 v[96:97], v[18:19], -1.0 op_sel_hi:[1,0]
	v_pk_fma_f32 v[90:91], v[4:5], v[90:91], 1.0 op_sel_hi:[1,1,0]
	v_pk_fma_f32 v[96:97], v[6:7], v[96:97], 1.0 op_sel_hi:[1,1,0]
	v_pk_mul_f32 v[90:91], v[28:29], v[90:91]
	v_pk_mul_f32 v[96:97], v[30:31], v[96:97]
	v_pk_mul_f32 v[28:29], v[24:25], v[90:91]
	v_pk_mul_f32 v[30:31], v[26:27], v[96:97]
	v_pk_mul_f32 v[28:29], v[8:9], v[28:29]
	v_pk_mul_f32 v[30:31], v[10:11], v[30:31]
	v_add_f32_e32 v28, v28, v29
	v_add_f32_e32 v29, v30, v31
	v_add_f32_e32 v28, v28, v29
	v_add_f32_dpp v42, v42, v42 quad_perm:[1,0,3,2] row_mask:0xf bank_mask:0xf bound_ctrl:1
	s_nop 0
	v_add_f32_dpp v28, v28, v28 quad_perm:[1,0,3,2] row_mask:0xf bank_mask:0xf bound_ctrl:1
	v_add_f32_dpp v42, v42, v42 quad_perm:[2,3,0,1] row_mask:0xf bank_mask:0xf bound_ctrl:1
	s_nop 0
	v_add_f32_dpp v28, v28, v28 quad_perm:[2,3,0,1] row_mask:0xf bank_mask:0xf bound_ctrl:1
	v_add_f32_dpp v42, v42, v42 row_half_mirror row_mask:0xf bank_mask:0xf bound_ctrl:1
	s_nop 0
	v_add_f32_dpp v28, v28, v28 row_half_mirror row_mask:0xf bank_mask:0xf bound_ctrl:1
	v_mov_b32_dpp v47, v42 row_mirror row_mask:0xf bank_mask:0xf bound_ctrl:1
	s_nop 0
	v_mov_b32_dpp v29, v28 row_mirror row_mask:0xf bank_mask:0xf bound_ctrl:1
	s_and_saveexec_b64 s[12:13], s[6:7]
	s_cbranch_execz .LBB0_442
	s_add_i32 s94, s94, 48
	v_cmp_lt_u32_e32 vcc, s94, v106
	s_and_b64 exec, exec, vcc
	s_cbranch_execz .LBB0_442
	v_add_f32_e32 v30, v28, v29
	v_add_u32_e32 v28, s94, v46
	v_ashrrev_i32_e32 v29, 31, v28
	v_lshlrev_b64 v[28:29], 6, v[28:29]
	v_lshl_add_u64 v[28:29], s[58:59], 0, v[28:29]
	global_store_dword v[28:29], v30, off
